# late-scan prefetch: helper waves touch XB and WIN rows 3584.. (next phase's GEMM operands) once per 64B line in scan intervals 48-58 so they are cache-resident for the conv/gate GEMM
# speedup vs baseline: 1.0064x; 1.0064x over previous
.Lcv_noitem:
	s_sub_u32 s54, s12, 48
	s_cmp_lt_u32 s54, 11
	s_cbranch_scc0 .Lpf_skip
	s_lshl_b32 s54, s54, 10
	s_lshl_b32 s53, s8, 2
	s_add_i32 s53, s53, s11
	s_add_i32 s53, s53, -4
	s_add_i32 s54, s54, s53
	s_cmp_lt_u32 s54, 0x2a00
	s_cbranch_scc0 .Lpf_skip
	s_cmp_lt_u32 s54, 0x2080
	s_cbranch_scc0 .Lpf_win
	s_lshl_b32 s55, s54, 12
	s_add_u32 s56, s84, s55
	s_addc_u32 s57, s85, 0
	s_branch .Lpf_go
.Lpf_win:
	s_sub_u32 s55, s54, 0x2080
	s_lshl_b32 s55, s55, 12
	s_add_u32 s56, s86, 0x1780000
	s_addc_u32 s57, s87, 0
	s_add_u32 s56, s56, s55
	s_addc_u32 s57, s57, 0
.Lpf_go:
	v_lshlrev_b32_e32 v84, 6, v231
	global_load_dword v242, v84, s[56:57]
